# v126 with the f32 beta/alpha GEMV items on the f32 matrix cores (v_mfma_f32_16x16x4_f32, f32 operands and accumulate; nonlinearity once on 32 lanes instead of 16 sequential rows)
# speedup vs baseline: 1.0024x; 1.0024x over previous
; __device__ __forceinline__ float bf2f(bfu h) { return __uint_as_float(((unsigned)h) << 16); }
; #define SHX(v, m) shx_((v), (m), lane)
; __device__ __forceinline__ int ptid_(int wave) { int l_; asm volatile("v_mbcnt_lo_u32_b32 %0, -1, 0\n\tv_mbcnt_hi_u32_b32 %0, -1, %0" : "=v"(l_)); return (wave << 6) | l_; }
; __device__ void ba_item(const Params& p, int L, int rp) {
;     ...
;   const float* wba = misc + MF_WBA + (L >> 1) * 8192;
;   const float* rowss = misc + MF_RSP + (L == 0 ? 0L : 2L * MTOK * 16);
;   int tid = ptid_(p.tid); asm volatile("" : "+v"(tid));
;   const int wid = tid >> 6, lane = tid & 63;
;   f32x4 wr_[8][4];
;   _Pragma("unroll") for (int j = 0; j < 8; ++j) _Pragma("unroll") for (int e4 = 0; e4 < 4; ++e4)
;     wr_[j][e4] = *(const f32x4*)(wba + j * 1024 + lane * 16 + e4 * 4);
;   for (int bt = 0; bt < 8; ++bt) {
;     bf16x8 h0[2], h1[2]; f32x4 ps[2][4];
;     _Pragma("unroll") for (int u = 0; u < 2; ++u) {
;       const int row = rp * 128 + wid * 16 + bt * 2 + u;
;       const bfu* hr = hb + (long)row * 1024 + lane * 16;
;       h0[u] = *(const bf16x8*)hr; h1[u] = *(const bf16x8*)(hr + 8);
;       _Pragma("unroll") for (int i = 0; i < 4; ++i) ps[u][i] = *(const f32x4*)(rowss + (long)row * 16 + i * 4);
;     }
;     _Pragma("unroll") for (int u = 0; u < 2; ++u) {
;       const int row = rp * 128 + wid * 16 + bt * 2 + u;
;       float hf[16];
;       _Pragma("unroll") for (int e = 0; e < 8; ++e) { hf[e] = bf2f((bfu)h0[u][e]); hf[8 + e] = bf2f((bfu)h1[u][e]); }
;       float a[8];
;       _Pragma("unroll") for (int j = 0; j < 8; ++j) {
;         float s = 0.f;
;         _Pragma("unroll") for (int e4 = 0; e4 < 4; ++e4) _Pragma("unroll") for (int e = 0; e < 4; ++e) s += hf[e4 * 4 + e] * wr_[j][e4][e];
;         _Pragma("unroll") for (int o = 32; o >= 1; o >>= 1) s += SHX(s, o);
;         a[j] = s;
;       }
.LBB0_612:
	s_cmpk_gt_i32 s18, 0x6ff
	s_mov_b64 s[0:1], -1
	s_cbranch_scc0 .LBB0_628
	v_mbcnt_lo_u32_b32 v0, -1, 0
	v_mbcnt_hi_u32_b32 v0, -1, v0
	s_waitcnt vmcnt(0)
	v_readlane_b32 s24, v254, 62
	v_readlane_b32 s25, v254, 63
	s_lshr_b32 s2, s33, 2
	s_add_i32 s2, s2, s20
	s_add_i32 s2, s2, 0xfffc8000
	v_and_b32_e32 v2, 15, v0
	v_lshrrev_b32_e32 v3, 4, v0
	v_add_u32_e32 v152, s2, v2
	v_lshlrev_b32_e32 v152, 11, v152
	v_lshl_add_u32 v152, v3, 4, v152
	v_mov_b32_e32 v153, 0
	v_lshl_add_u64 v[4:5], s[80:81], 0, v[152:153]
	v_and_b32_e32 v152, 7, v2
	v_lshlrev_b32_e32 v152, 12, v152
	v_lshl_add_u32 v152, v3, 5, v152
	v_lshl_add_u64 v[6:7], s[26:27], 0, v[152:153]
	v_lshl_add_u32 v152, v3, 2, s2
	v_lshlrev_b32_e32 v152, 6, v152
	v_lshl_add_u64 v[144:145], s[24:25], 0, v[152:153]
	v_and_b32_e32 v146, 7, v2
	v_max_u32_e32 v152, 4, v146
	v_add_u32_e32 v152, s19, v152
	v_lshlrev_b32_e32 v152, 2, v152
	v_readlane_b32 s92, v254, 0
	v_readlane_b32 s93, v254, 1
	v_readlane_b32 s94, v254, 2
	v_readlane_b32 s95, v254, 3
	v_readlane_b32 s0, v252, 18
	v_readlane_b32 s1, v252, 19
	v_lshl_add_u32 v154, v3, 2, s2
	v_lshlrev_b32_e32 v154, 5, v154
	v_lshl_add_u32 v154, v146, 2, v154
	v_mov_b32_e32 v155, 0
	v_lshl_add_u64 v[148:149], s[0:1], 0, v[154:155]
	global_load_dword v150, v152, s[94:95]
	global_load_dword v151, v152, s[92:93]
	global_load_dwordx4 v[80:83], v[144:145], off offset:0
	global_load_dwordx4 v[84:87], v[144:145], off offset:16
	global_load_dwordx4 v[88:91], v[144:145], off offset:32
	global_load_dwordx4 v[92:95], v[144:145], off offset:48
	global_load_dwordx4 v[96:99], v[144:145], off offset:64
	global_load_dwordx4 v[100:103], v[144:145], off offset:80
	global_load_dwordx4 v[104:107], v[144:145], off offset:96
	global_load_dwordx4 v[108:111], v[144:145], off offset:112
	global_load_dwordx4 v[112:115], v[144:145], off offset:128
	global_load_dwordx4 v[116:119], v[144:145], off offset:144
	global_load_dwordx4 v[120:123], v[144:145], off offset:160
	global_load_dwordx4 v[124:127], v[144:145], off offset:176
	global_load_dwordx4 v[128:131], v[144:145], off offset:192
	global_load_dwordx4 v[132:135], v[144:145], off offset:208
	global_load_dwordx4 v[136:139], v[144:145], off offset:224
	global_load_dwordx4 v[140:143], v[144:145], off offset:240
	v_mov_b32_e32 v8, 0
	v_mov_b32_e32 v9, 0
	v_mov_b32_e32 v10, 0
	v_mov_b32_e32 v11, 0
	global_load_dwordx4 v[16:19], v[4:5], off
	global_load_dwordx4 v[20:23], v[6:7], off
	global_load_dwordx4 v[24:27], v[6:7], off offset:16
	global_load_dwordx4 v[28:31], v[4:5], off offset:64
	global_load_dwordx4 v[32:35], v[6:7], off offset:128
	global_load_dwordx4 v[36:39], v[6:7], off offset:144
	global_load_dwordx4 v[40:43], v[4:5], off offset:128
	global_load_dwordx4 v[44:47], v[6:7], off offset:256
	global_load_dwordx4 v[48:51], v[6:7], off offset:272
	global_load_dwordx4 v[52:55], v[4:5], off offset:192
	global_load_dwordx4 v[56:59], v[6:7], off offset:384
	global_load_dwordx4 v[60:63], v[6:7], off offset:400
	s_waitcnt vmcnt(9)
	v_lshlrev_b32_e32 v64, 16, v16
	v_and_b32_e32 v65, 0xffff0000, v16
	v_lshlrev_b32_e32 v66, 16, v17
	v_and_b32_e32 v67, 0xffff0000, v17
	v_lshlrev_b32_e32 v68, 16, v18
	v_and_b32_e32 v69, 0xffff0000, v18
	v_lshlrev_b32_e32 v70, 16, v19
	v_and_b32_e32 v71, 0xffff0000, v19
	v_mfma_f32_16x16x4_f32 v[8:11], v64, v20, v[8:11]
	v_mfma_f32_16x16x4_f32 v[8:11], v65, v21, v[8:11]
	v_mfma_f32_16x16x4_f32 v[8:11], v66, v22, v[8:11]
	v_mfma_f32_16x16x4_f32 v[8:11], v67, v23, v[8:11]
	v_mfma_f32_16x16x4_f32 v[8:11], v68, v24, v[8:11]
	v_mfma_f32_16x16x4_f32 v[8:11], v69, v25, v[8:11]
	v_mfma_f32_16x16x4_f32 v[8:11], v70, v26, v[8:11]
	v_mfma_f32_16x16x4_f32 v[8:11], v71, v27, v[8:11]
	global_load_dwordx4 v[16:19], v[4:5], off offset:256
	global_load_dwordx4 v[20:23], v[6:7], off offset:512
	global_load_dwordx4 v[24:27], v[6:7], off offset:528
	s_waitcnt vmcnt(9)
	v_lshlrev_b32_e32 v64, 16, v28
	v_and_b32_e32 v65, 0xffff0000, v28
	v_lshlrev_b32_e32 v66, 16, v29
	v_and_b32_e32 v67, 0xffff0000, v29
	v_lshlrev_b32_e32 v68, 16, v30
	v_and_b32_e32 v69, 0xffff0000, v30
	v_lshlrev_b32_e32 v70, 16, v31
	v_and_b32_e32 v71, 0xffff0000, v31
	v_mfma_f32_16x16x4_f32 v[8:11], v64, v32, v[8:11]
	v_mfma_f32_16x16x4_f32 v[8:11], v65, v33, v[8:11]
	v_mfma_f32_16x16x4_f32 v[8:11], v66, v34, v[8:11]
	v_mfma_f32_16x16x4_f32 v[8:11], v67, v35, v[8:11]
	v_mfma_f32_16x16x4_f32 v[8:11], v68, v36, v[8:11]
	v_mfma_f32_16x16x4_f32 v[8:11], v69, v37, v[8:11]
	v_mfma_f32_16x16x4_f32 v[8:11], v70, v38, v[8:11]
	v_mfma_f32_16x16x4_f32 v[8:11], v71, v39, v[8:11]
	global_load_dwordx4 v[28:31], v[4:5], off offset:320
	global_load_dwordx4 v[32:35], v[6:7], off offset:640
	global_load_dwordx4 v[36:39], v[6:7], off offset:656
	s_waitcnt vmcnt(9)
	v_lshlrev_b32_e32 v64, 16, v40
	v_and_b32_e32 v65, 0xffff0000, v40
	v_lshlrev_b32_e32 v66, 16, v41
	v_and_b32_e32 v67, 0xffff0000, v41
	v_lshlrev_b32_e32 v68, 16, v42
	v_and_b32_e32 v69, 0xffff0000, v42
	v_lshlrev_b32_e32 v70, 16, v43
	v_and_b32_e32 v71, 0xffff0000, v43
	v_mfma_f32_16x16x4_f32 v[8:11], v64, v44, v[8:11]
	v_mfma_f32_16x16x4_f32 v[8:11], v65, v45, v[8:11]
	v_mfma_f32_16x16x4_f32 v[8:11], v66, v46, v[8:11]
	v_mfma_f32_16x16x4_f32 v[8:11], v67, v47, v[8:11]
	v_mfma_f32_16x16x4_f32 v[8:11], v68, v48, v[8:11]
	v_mfma_f32_16x16x4_f32 v[8:11], v69, v49, v[8:11]
	v_mfma_f32_16x16x4_f32 v[8:11], v70, v50, v[8:11]
	v_mfma_f32_16x16x4_f32 v[8:11], v71, v51, v[8:11]
	global_load_dwordx4 v[40:43], v[4:5], off offset:384
	global_load_dwordx4 v[44:47], v[6:7], off offset:768
	global_load_dwordx4 v[48:51], v[6:7], off offset:784
	s_waitcnt vmcnt(9)
; __device__ __forceinline__ float bf2f(bfu h) { return __uint_as_float(((unsigned)h) << 16); }
; #define SHX(v, m) shx_((v), (m), lane)
; __device__ void ba_item(const Params& p, int L, int rp) {
;     ...
;       _Pragma("unroll") for (int e = 0; e < 8; ++e) { hf[e] = bf2f((bfu)h0[u][e]); hf[8 + e] = bf2f((bfu)h1[u][e]); }
;       float a[8];
;       _Pragma("unroll") for (int j = 0; j < 8; ++j) {
;         float s = 0.f;
;         _Pragma("unroll") for (int e4 = 0; e4 < 4; ++e4) _Pragma("unroll") for (int e = 0; e < 4; ++e) s += hf[e4 * 4 + e] * wr_[j][e4][e];
;         _Pragma("unroll") for (int o = 32; o >= 1; o >>= 1) s += SHX(s, o);
;         a[j] = s;
	v_lshlrev_b32_e32 v64, 16, v52
	v_and_b32_e32 v65, 0xffff0000, v52
	v_lshlrev_b32_e32 v66, 16, v53
	v_and_b32_e32 v67, 0xffff0000, v53
	v_lshlrev_b32_e32 v68, 16, v54
	v_and_b32_e32 v69, 0xffff0000, v54
	v_lshlrev_b32_e32 v70, 16, v55
	v_and_b32_e32 v71, 0xffff0000, v55
	v_mfma_f32_16x16x4_f32 v[8:11], v64, v56, v[8:11]
	v_mfma_f32_16x16x4_f32 v[8:11], v65, v57, v[8:11]
	v_mfma_f32_16x16x4_f32 v[8:11], v66, v58, v[8:11]
	v_mfma_f32_16x16x4_f32 v[8:11], v67, v59, v[8:11]
	v_mfma_f32_16x16x4_f32 v[8:11], v68, v60, v[8:11]
	v_mfma_f32_16x16x4_f32 v[8:11], v69, v61, v[8:11]
	v_mfma_f32_16x16x4_f32 v[8:11], v70, v62, v[8:11]
	v_mfma_f32_16x16x4_f32 v[8:11], v71, v63, v[8:11]
	global_load_dwordx4 v[52:55], v[4:5], off offset:448
	global_load_dwordx4 v[56:59], v[6:7], off offset:896
	global_load_dwordx4 v[60:63], v[6:7], off offset:912
	s_waitcnt vmcnt(9)
	v_lshlrev_b32_e32 v64, 16, v16
	v_and_b32_e32 v65, 0xffff0000, v16
	v_lshlrev_b32_e32 v66, 16, v17
	v_and_b32_e32 v67, 0xffff0000, v17
	v_lshlrev_b32_e32 v68, 16, v18
	v_and_b32_e32 v69, 0xffff0000, v18
	v_lshlrev_b32_e32 v70, 16, v19
	v_and_b32_e32 v71, 0xffff0000, v19
	v_mfma_f32_16x16x4_f32 v[8:11], v64, v20, v[8:11]
	v_mfma_f32_16x16x4_f32 v[8:11], v65, v21, v[8:11]
	v_mfma_f32_16x16x4_f32 v[8:11], v66, v22, v[8:11]
	v_mfma_f32_16x16x4_f32 v[8:11], v67, v23, v[8:11]
	v_mfma_f32_16x16x4_f32 v[8:11], v68, v24, v[8:11]
	v_mfma_f32_16x16x4_f32 v[8:11], v69, v25, v[8:11]
	v_mfma_f32_16x16x4_f32 v[8:11], v70, v26, v[8:11]
	v_mfma_f32_16x16x4_f32 v[8:11], v71, v27, v[8:11]
	global_load_dwordx4 v[16:19], v[4:5], off offset:512
	global_load_dwordx4 v[20:23], v[6:7], off offset:1024
	global_load_dwordx4 v[24:27], v[6:7], off offset:1040
	s_waitcnt vmcnt(9)
	v_lshlrev_b32_e32 v64, 16, v28
	v_and_b32_e32 v65, 0xffff0000, v28
	v_lshlrev_b32_e32 v66, 16, v29
	v_and_b32_e32 v67, 0xffff0000, v29
	v_lshlrev_b32_e32 v68, 16, v30
	v_and_b32_e32 v69, 0xffff0000, v30
	v_lshlrev_b32_e32 v70, 16, v31
	v_and_b32_e32 v71, 0xffff0000, v31
	v_mfma_f32_16x16x4_f32 v[8:11], v64, v32, v[8:11]
	v_mfma_f32_16x16x4_f32 v[8:11], v65, v33, v[8:11]
	v_mfma_f32_16x16x4_f32 v[8:11], v66, v34, v[8:11]
	v_mfma_f32_16x16x4_f32 v[8:11], v67, v35, v[8:11]
	v_mfma_f32_16x16x4_f32 v[8:11], v68, v36, v[8:11]
	v_mfma_f32_16x16x4_f32 v[8:11], v69, v37, v[8:11]
	v_mfma_f32_16x16x4_f32 v[8:11], v70, v38, v[8:11]
	v_mfma_f32_16x16x4_f32 v[8:11], v71, v39, v[8:11]
	global_load_dwordx4 v[28:31], v[4:5], off offset:576
	global_load_dwordx4 v[32:35], v[6:7], off offset:1152
	global_load_dwordx4 v[36:39], v[6:7], off offset:1168
	s_waitcnt vmcnt(9)
	v_lshlrev_b32_e32 v64, 16, v40
	v_and_b32_e32 v65, 0xffff0000, v40
	v_lshlrev_b32_e32 v66, 16, v41
	v_and_b32_e32 v67, 0xffff0000, v41
	v_lshlrev_b32_e32 v68, 16, v42
	v_and_b32_e32 v69, 0xffff0000, v42
	v_lshlrev_b32_e32 v70, 16, v43
	v_and_b32_e32 v71, 0xffff0000, v43
	v_mfma_f32_16x16x4_f32 v[8:11], v64, v44, v[8:11]
	v_mfma_f32_16x16x4_f32 v[8:11], v65, v45, v[8:11]
	v_mfma_f32_16x16x4_f32 v[8:11], v66, v46, v[8:11]
	v_mfma_f32_16x16x4_f32 v[8:11], v67, v47, v[8:11]
	v_mfma_f32_16x16x4_f32 v[8:11], v68, v48, v[8:11]
	v_mfma_f32_16x16x4_f32 v[8:11], v69, v49, v[8:11]
	v_mfma_f32_16x16x4_f32 v[8:11], v70, v50, v[8:11]
	v_mfma_f32_16x16x4_f32 v[8:11], v71, v51, v[8:11]
	global_load_dwordx4 v[40:43], v[4:5], off offset:640
	global_load_dwordx4 v[44:47], v[6:7], off offset:1280
	global_load_dwordx4 v[48:51], v[6:7], off offset:1296
	s_waitcnt vmcnt(9)
	v_lshlrev_b32_e32 v64, 16, v52
	v_and_b32_e32 v65, 0xffff0000, v52
	v_lshlrev_b32_e32 v66, 16, v53
	v_and_b32_e32 v67, 0xffff0000, v53
	v_lshlrev_b32_e32 v68, 16, v54
	v_and_b32_e32 v69, 0xffff0000, v54
	v_lshlrev_b32_e32 v70, 16, v55
	v_and_b32_e32 v71, 0xffff0000, v55
	v_mfma_f32_16x16x4_f32 v[8:11], v64, v56, v[8:11]
	v_mfma_f32_16x16x4_f32 v[8:11], v65, v57, v[8:11]
	v_mfma_f32_16x16x4_f32 v[8:11], v66, v58, v[8:11]
	v_mfma_f32_16x16x4_f32 v[8:11], v67, v59, v[8:11]
	v_mfma_f32_16x16x4_f32 v[8:11], v68, v60, v[8:11]
	v_mfma_f32_16x16x4_f32 v[8:11], v69, v61, v[8:11]
	v_mfma_f32_16x16x4_f32 v[8:11], v70, v62, v[8:11]
	v_mfma_f32_16x16x4_f32 v[8:11], v71, v63, v[8:11]
	global_load_dwordx4 v[52:55], v[4:5], off offset:704
	global_load_dwordx4 v[56:59], v[6:7], off offset:1408
	global_load_dwordx4 v[60:63], v[6:7], off offset:1424
	s_waitcnt vmcnt(9)
	v_lshlrev_b32_e32 v64, 16, v16
	v_and_b32_e32 v65, 0xffff0000, v16
	v_lshlrev_b32_e32 v66, 16, v17
	v_and_b32_e32 v67, 0xffff0000, v17
	v_lshlrev_b32_e32 v68, 16, v18
	v_and_b32_e32 v69, 0xffff0000, v18
	v_lshlrev_b32_e32 v70, 16, v19
	v_and_b32_e32 v71, 0xffff0000, v19
	v_mfma_f32_16x16x4_f32 v[8:11], v64, v20, v[8:11]
	v_mfma_f32_16x16x4_f32 v[8:11], v65, v21, v[8:11]
	v_mfma_f32_16x16x4_f32 v[8:11], v66, v22, v[8:11]
	v_mfma_f32_16x16x4_f32 v[8:11], v67, v23, v[8:11]
	v_mfma_f32_16x16x4_f32 v[8:11], v68, v24, v[8:11]
	v_mfma_f32_16x16x4_f32 v[8:11], v69, v25, v[8:11]
	v_mfma_f32_16x16x4_f32 v[8:11], v70, v26, v[8:11]
	v_mfma_f32_16x16x4_f32 v[8:11], v71, v27, v[8:11]
	global_load_dwordx4 v[16:19], v[4:5], off offset:768
	global_load_dwordx4 v[20:23], v[6:7], off offset:1536
	global_load_dwordx4 v[24:27], v[6:7], off offset:1552
	s_waitcnt vmcnt(9)
	v_lshlrev_b32_e32 v64, 16, v28
	v_and_b32_e32 v65, 0xffff0000, v28
	v_lshlrev_b32_e32 v66, 16, v29
	v_and_b32_e32 v67, 0xffff0000, v29
	v_lshlrev_b32_e32 v68, 16, v30
	v_and_b32_e32 v69, 0xffff0000, v30
	v_lshlrev_b32_e32 v70, 16, v31
	v_and_b32_e32 v71, 0xffff0000, v31
	v_mfma_f32_16x16x4_f32 v[8:11], v64, v32, v[8:11]
	v_mfma_f32_16x16x4_f32 v[8:11], v65, v33, v[8:11]
	v_mfma_f32_16x16x4_f32 v[8:11], v66, v34, v[8:11]
	v_mfma_f32_16x16x4_f32 v[8:11], v67, v35, v[8:11]
	v_mfma_f32_16x16x4_f32 v[8:11], v68, v36, v[8:11]
	v_mfma_f32_16x16x4_f32 v[8:11], v69, v37, v[8:11]
	v_mfma_f32_16x16x4_f32 v[8:11], v70, v38, v[8:11]
	v_mfma_f32_16x16x4_f32 v[8:11], v71, v39, v[8:11]
	global_load_dwordx4 v[28:31], v[4:5], off offset:832
	global_load_dwordx4 v[32:35], v[6:7], off offset:1664
	global_load_dwordx4 v[36:39], v[6:7], off offset:1680
	s_waitcnt vmcnt(9)
; __device__ __forceinline__ float bf2f(bfu h) { return __uint_as_float(((unsigned)h) << 16); }
; #define SHX(v, m) shx_((v), (m), lane)
; __device__ void ba_item(const Params& p, int L, int rp) {
;     ...
;       _Pragma("unroll") for (int e = 0; e < 8; ++e) { hf[e] = bf2f((bfu)h0[u][e]); hf[8 + e] = bf2f((bfu)h1[u][e]); }
;       float a[8];
;       _Pragma("unroll") for (int j = 0; j < 8; ++j) {
;         float s = 0.f;
;         _Pragma("unroll") for (int e4 = 0; e4 < 4; ++e4) _Pragma("unroll") for (int e = 0; e < 4; ++e) s += hf[e4 * 4 + e] * wr_[j][e4][e];
;         _Pragma("unroll") for (int o = 32; o >= 1; o >>= 1) s += SHX(s, o);
;         a[j] = s;
	v_lshlrev_b32_e32 v64, 16, v40
	v_and_b32_e32 v65, 0xffff0000, v40
	v_lshlrev_b32_e32 v66, 16, v41
	v_and_b32_e32 v67, 0xffff0000, v41
	v_lshlrev_b32_e32 v68, 16, v42
	v_and_b32_e32 v69, 0xffff0000, v42
	v_lshlrev_b32_e32 v70, 16, v43
	v_and_b32_e32 v71, 0xffff0000, v43
	v_mfma_f32_16x16x4_f32 v[8:11], v64, v44, v[8:11]
	v_mfma_f32_16x16x4_f32 v[8:11], v65, v45, v[8:11]
	v_mfma_f32_16x16x4_f32 v[8:11], v66, v46, v[8:11]
	v_mfma_f32_16x16x4_f32 v[8:11], v67, v47, v[8:11]
	v_mfma_f32_16x16x4_f32 v[8:11], v68, v48, v[8:11]
	v_mfma_f32_16x16x4_f32 v[8:11], v69, v49, v[8:11]
	v_mfma_f32_16x16x4_f32 v[8:11], v70, v50, v[8:11]
	v_mfma_f32_16x16x4_f32 v[8:11], v71, v51, v[8:11]
	global_load_dwordx4 v[40:43], v[4:5], off offset:896
	global_load_dwordx4 v[44:47], v[6:7], off offset:1792
	global_load_dwordx4 v[48:51], v[6:7], off offset:1808
	s_waitcnt vmcnt(9)
	v_lshlrev_b32_e32 v64, 16, v52
	v_and_b32_e32 v65, 0xffff0000, v52
	v_lshlrev_b32_e32 v66, 16, v53
	v_and_b32_e32 v67, 0xffff0000, v53
	v_lshlrev_b32_e32 v68, 16, v54
	v_and_b32_e32 v69, 0xffff0000, v54
	v_lshlrev_b32_e32 v70, 16, v55
	v_and_b32_e32 v71, 0xffff0000, v55
	v_mfma_f32_16x16x4_f32 v[8:11], v64, v56, v[8:11]
	v_mfma_f32_16x16x4_f32 v[8:11], v65, v57, v[8:11]
	v_mfma_f32_16x16x4_f32 v[8:11], v66, v58, v[8:11]
	v_mfma_f32_16x16x4_f32 v[8:11], v67, v59, v[8:11]
	v_mfma_f32_16x16x4_f32 v[8:11], v68, v60, v[8:11]
	v_mfma_f32_16x16x4_f32 v[8:11], v69, v61, v[8:11]
	v_mfma_f32_16x16x4_f32 v[8:11], v70, v62, v[8:11]
	v_mfma_f32_16x16x4_f32 v[8:11], v71, v63, v[8:11]
	global_load_dwordx4 v[52:55], v[4:5], off offset:960
	global_load_dwordx4 v[56:59], v[6:7], off offset:1920
	global_load_dwordx4 v[60:63], v[6:7], off offset:1936
	s_waitcnt vmcnt(9)
	v_lshlrev_b32_e32 v64, 16, v16
	v_and_b32_e32 v65, 0xffff0000, v16
	v_lshlrev_b32_e32 v66, 16, v17
	v_and_b32_e32 v67, 0xffff0000, v17
	v_lshlrev_b32_e32 v68, 16, v18
	v_and_b32_e32 v69, 0xffff0000, v18
	v_lshlrev_b32_e32 v70, 16, v19
	v_and_b32_e32 v71, 0xffff0000, v19
	v_mfma_f32_16x16x4_f32 v[8:11], v64, v20, v[8:11]
	v_mfma_f32_16x16x4_f32 v[8:11], v65, v21, v[8:11]
	v_mfma_f32_16x16x4_f32 v[8:11], v66, v22, v[8:11]
	v_mfma_f32_16x16x4_f32 v[8:11], v67, v23, v[8:11]
	v_mfma_f32_16x16x4_f32 v[8:11], v68, v24, v[8:11]
	v_mfma_f32_16x16x4_f32 v[8:11], v69, v25, v[8:11]
	v_mfma_f32_16x16x4_f32 v[8:11], v70, v26, v[8:11]
	v_mfma_f32_16x16x4_f32 v[8:11], v71, v27, v[8:11]
	global_load_dwordx4 v[16:19], v[4:5], off offset:1024
	global_load_dwordx4 v[20:23], v[6:7], off offset:2048
	global_load_dwordx4 v[24:27], v[6:7], off offset:2064
	s_waitcnt vmcnt(9)
	v_lshlrev_b32_e32 v64, 16, v28
	v_and_b32_e32 v65, 0xffff0000, v28
	v_lshlrev_b32_e32 v66, 16, v29
	v_and_b32_e32 v67, 0xffff0000, v29
	v_lshlrev_b32_e32 v68, 16, v30
	v_and_b32_e32 v69, 0xffff0000, v30
	v_lshlrev_b32_e32 v70, 16, v31
	v_and_b32_e32 v71, 0xffff0000, v31
	v_mfma_f32_16x16x4_f32 v[8:11], v64, v32, v[8:11]
	v_mfma_f32_16x16x4_f32 v[8:11], v65, v33, v[8:11]
	v_mfma_f32_16x16x4_f32 v[8:11], v66, v34, v[8:11]
	v_mfma_f32_16x16x4_f32 v[8:11], v67, v35, v[8:11]
	v_mfma_f32_16x16x4_f32 v[8:11], v68, v36, v[8:11]
	v_mfma_f32_16x16x4_f32 v[8:11], v69, v37, v[8:11]
	v_mfma_f32_16x16x4_f32 v[8:11], v70, v38, v[8:11]
	v_mfma_f32_16x16x4_f32 v[8:11], v71, v39, v[8:11]
	global_load_dwordx4 v[28:31], v[4:5], off offset:1088
	global_load_dwordx4 v[32:35], v[6:7], off offset:2176
	global_load_dwordx4 v[36:39], v[6:7], off offset:2192
	s_waitcnt vmcnt(9)
	v_lshlrev_b32_e32 v64, 16, v40
	v_and_b32_e32 v65, 0xffff0000, v40
	v_lshlrev_b32_e32 v66, 16, v41
	v_and_b32_e32 v67, 0xffff0000, v41
	v_lshlrev_b32_e32 v68, 16, v42
	v_and_b32_e32 v69, 0xffff0000, v42
	v_lshlrev_b32_e32 v70, 16, v43
	v_and_b32_e32 v71, 0xffff0000, v43
	v_mfma_f32_16x16x4_f32 v[8:11], v64, v44, v[8:11]
	v_mfma_f32_16x16x4_f32 v[8:11], v65, v45, v[8:11]
	v_mfma_f32_16x16x4_f32 v[8:11], v66, v46, v[8:11]
	v_mfma_f32_16x16x4_f32 v[8:11], v67, v47, v[8:11]
	v_mfma_f32_16x16x4_f32 v[8:11], v68, v48, v[8:11]
	v_mfma_f32_16x16x4_f32 v[8:11], v69, v49, v[8:11]
	v_mfma_f32_16x16x4_f32 v[8:11], v70, v50, v[8:11]
	v_mfma_f32_16x16x4_f32 v[8:11], v71, v51, v[8:11]
	global_load_dwordx4 v[40:43], v[4:5], off offset:1152
	global_load_dwordx4 v[44:47], v[6:7], off offset:2304
	global_load_dwordx4 v[48:51], v[6:7], off offset:2320
	s_waitcnt vmcnt(9)
	v_lshlrev_b32_e32 v64, 16, v52
	v_and_b32_e32 v65, 0xffff0000, v52
	v_lshlrev_b32_e32 v66, 16, v53
	v_and_b32_e32 v67, 0xffff0000, v53
	v_lshlrev_b32_e32 v68, 16, v54
	v_and_b32_e32 v69, 0xffff0000, v54
	v_lshlrev_b32_e32 v70, 16, v55
	v_and_b32_e32 v71, 0xffff0000, v55
	v_mfma_f32_16x16x4_f32 v[8:11], v64, v56, v[8:11]
	v_mfma_f32_16x16x4_f32 v[8:11], v65, v57, v[8:11]
	v_mfma_f32_16x16x4_f32 v[8:11], v66, v58, v[8:11]
	v_mfma_f32_16x16x4_f32 v[8:11], v67, v59, v[8:11]
	v_mfma_f32_16x16x4_f32 v[8:11], v68, v60, v[8:11]
	v_mfma_f32_16x16x4_f32 v[8:11], v69, v61, v[8:11]
	v_mfma_f32_16x16x4_f32 v[8:11], v70, v62, v[8:11]
	v_mfma_f32_16x16x4_f32 v[8:11], v71, v63, v[8:11]
	global_load_dwordx4 v[52:55], v[4:5], off offset:1216
	global_load_dwordx4 v[56:59], v[6:7], off offset:2432
	global_load_dwordx4 v[60:63], v[6:7], off offset:2448
	s_waitcnt vmcnt(9)
	v_lshlrev_b32_e32 v64, 16, v16
	v_and_b32_e32 v65, 0xffff0000, v16
	v_lshlrev_b32_e32 v66, 16, v17
	v_and_b32_e32 v67, 0xffff0000, v17
	v_lshlrev_b32_e32 v68, 16, v18
	v_and_b32_e32 v69, 0xffff0000, v18
	v_lshlrev_b32_e32 v70, 16, v19
	v_and_b32_e32 v71, 0xffff0000, v19
	v_mfma_f32_16x16x4_f32 v[8:11], v64, v20, v[8:11]
	v_mfma_f32_16x16x4_f32 v[8:11], v65, v21, v[8:11]
	v_mfma_f32_16x16x4_f32 v[8:11], v66, v22, v[8:11]
	v_mfma_f32_16x16x4_f32 v[8:11], v67, v23, v[8:11]
	v_mfma_f32_16x16x4_f32 v[8:11], v68, v24, v[8:11]
	v_mfma_f32_16x16x4_f32 v[8:11], v69, v25, v[8:11]
	v_mfma_f32_16x16x4_f32 v[8:11], v70, v26, v[8:11]
	v_mfma_f32_16x16x4_f32 v[8:11], v71, v27, v[8:11]
	global_load_dwordx4 v[16:19], v[4:5], off offset:1280
	global_load_dwordx4 v[20:23], v[6:7], off offset:2560
	global_load_dwordx4 v[24:27], v[6:7], off offset:2576
	s_waitcnt vmcnt(9)
; __device__ __forceinline__ float bf2f(bfu h) { return __uint_as_float(((unsigned)h) << 16); }
; #define SHX(v, m) shx_((v), (m), lane)
; __device__ void ba_item(const Params& p, int L, int rp) {
;     ...
;       _Pragma("unroll") for (int e = 0; e < 8; ++e) { hf[e] = bf2f((bfu)h0[u][e]); hf[8 + e] = bf2f((bfu)h1[u][e]); }
;       float a[8];
;       _Pragma("unroll") for (int j = 0; j < 8; ++j) {
;         float s = 0.f;
;         _Pragma("unroll") for (int e4 = 0; e4 < 4; ++e4) _Pragma("unroll") for (int e = 0; e < 4; ++e) s += hf[e4 * 4 + e] * wr_[j][e4][e];
;         _Pragma("unroll") for (int o = 32; o >= 1; o >>= 1) s += SHX(s, o);
;         a[j] = s;
	v_lshlrev_b32_e32 v64, 16, v28
	v_and_b32_e32 v65, 0xffff0000, v28
	v_lshlrev_b32_e32 v66, 16, v29
	v_and_b32_e32 v67, 0xffff0000, v29
	v_lshlrev_b32_e32 v68, 16, v30
	v_and_b32_e32 v69, 0xffff0000, v30
	v_lshlrev_b32_e32 v70, 16, v31
	v_and_b32_e32 v71, 0xffff0000, v31
	v_mfma_f32_16x16x4_f32 v[8:11], v64, v32, v[8:11]
	v_mfma_f32_16x16x4_f32 v[8:11], v65, v33, v[8:11]
	v_mfma_f32_16x16x4_f32 v[8:11], v66, v34, v[8:11]
	v_mfma_f32_16x16x4_f32 v[8:11], v67, v35, v[8:11]
	v_mfma_f32_16x16x4_f32 v[8:11], v68, v36, v[8:11]
	v_mfma_f32_16x16x4_f32 v[8:11], v69, v37, v[8:11]
	v_mfma_f32_16x16x4_f32 v[8:11], v70, v38, v[8:11]
	v_mfma_f32_16x16x4_f32 v[8:11], v71, v39, v[8:11]
	global_load_dwordx4 v[28:31], v[4:5], off offset:1344
	global_load_dwordx4 v[32:35], v[6:7], off offset:2688
	global_load_dwordx4 v[36:39], v[6:7], off offset:2704
	s_waitcnt vmcnt(9)
	v_lshlrev_b32_e32 v64, 16, v40
	v_and_b32_e32 v65, 0xffff0000, v40
	v_lshlrev_b32_e32 v66, 16, v41
	v_and_b32_e32 v67, 0xffff0000, v41
	v_lshlrev_b32_e32 v68, 16, v42
	v_and_b32_e32 v69, 0xffff0000, v42
	v_lshlrev_b32_e32 v70, 16, v43
	v_and_b32_e32 v71, 0xffff0000, v43
	v_mfma_f32_16x16x4_f32 v[8:11], v64, v44, v[8:11]
	v_mfma_f32_16x16x4_f32 v[8:11], v65, v45, v[8:11]
	v_mfma_f32_16x16x4_f32 v[8:11], v66, v46, v[8:11]
	v_mfma_f32_16x16x4_f32 v[8:11], v67, v47, v[8:11]
	v_mfma_f32_16x16x4_f32 v[8:11], v68, v48, v[8:11]
	v_mfma_f32_16x16x4_f32 v[8:11], v69, v49, v[8:11]
	v_mfma_f32_16x16x4_f32 v[8:11], v70, v50, v[8:11]
	v_mfma_f32_16x16x4_f32 v[8:11], v71, v51, v[8:11]
	global_load_dwordx4 v[40:43], v[4:5], off offset:1408
	global_load_dwordx4 v[44:47], v[6:7], off offset:2816
	global_load_dwordx4 v[48:51], v[6:7], off offset:2832
	s_waitcnt vmcnt(9)
	v_lshlrev_b32_e32 v64, 16, v52
	v_and_b32_e32 v65, 0xffff0000, v52
	v_lshlrev_b32_e32 v66, 16, v53
	v_and_b32_e32 v67, 0xffff0000, v53
	v_lshlrev_b32_e32 v68, 16, v54
	v_and_b32_e32 v69, 0xffff0000, v54
	v_lshlrev_b32_e32 v70, 16, v55
	v_and_b32_e32 v71, 0xffff0000, v55
	v_mfma_f32_16x16x4_f32 v[8:11], v64, v56, v[8:11]
	v_mfma_f32_16x16x4_f32 v[8:11], v65, v57, v[8:11]
	v_mfma_f32_16x16x4_f32 v[8:11], v66, v58, v[8:11]
	v_mfma_f32_16x16x4_f32 v[8:11], v67, v59, v[8:11]
	v_mfma_f32_16x16x4_f32 v[8:11], v68, v60, v[8:11]
	v_mfma_f32_16x16x4_f32 v[8:11], v69, v61, v[8:11]
	v_mfma_f32_16x16x4_f32 v[8:11], v70, v62, v[8:11]
	v_mfma_f32_16x16x4_f32 v[8:11], v71, v63, v[8:11]
	global_load_dwordx4 v[52:55], v[4:5], off offset:1472
	global_load_dwordx4 v[56:59], v[6:7], off offset:2944
	global_load_dwordx4 v[60:63], v[6:7], off offset:2960
	s_waitcnt vmcnt(9)
	v_lshlrev_b32_e32 v64, 16, v16
	v_and_b32_e32 v65, 0xffff0000, v16
	v_lshlrev_b32_e32 v66, 16, v17
	v_and_b32_e32 v67, 0xffff0000, v17
	v_lshlrev_b32_e32 v68, 16, v18
	v_and_b32_e32 v69, 0xffff0000, v18
	v_lshlrev_b32_e32 v70, 16, v19
	v_and_b32_e32 v71, 0xffff0000, v19
	v_mfma_f32_16x16x4_f32 v[8:11], v64, v20, v[8:11]
	v_mfma_f32_16x16x4_f32 v[8:11], v65, v21, v[8:11]
	v_mfma_f32_16x16x4_f32 v[8:11], v66, v22, v[8:11]
	v_mfma_f32_16x16x4_f32 v[8:11], v67, v23, v[8:11]
	v_mfma_f32_16x16x4_f32 v[8:11], v68, v24, v[8:11]
	v_mfma_f32_16x16x4_f32 v[8:11], v69, v25, v[8:11]
	v_mfma_f32_16x16x4_f32 v[8:11], v70, v26, v[8:11]
	v_mfma_f32_16x16x4_f32 v[8:11], v71, v27, v[8:11]
	global_load_dwordx4 v[16:19], v[4:5], off offset:1536
	global_load_dwordx4 v[20:23], v[6:7], off offset:3072
	global_load_dwordx4 v[24:27], v[6:7], off offset:3088
	s_waitcnt vmcnt(9)
	v_lshlrev_b32_e32 v64, 16, v28
	v_and_b32_e32 v65, 0xffff0000, v28
	v_lshlrev_b32_e32 v66, 16, v29
	v_and_b32_e32 v67, 0xffff0000, v29
	v_lshlrev_b32_e32 v68, 16, v30
	v_and_b32_e32 v69, 0xffff0000, v30
	v_lshlrev_b32_e32 v70, 16, v31
	v_and_b32_e32 v71, 0xffff0000, v31
	v_mfma_f32_16x16x4_f32 v[8:11], v64, v32, v[8:11]
	v_mfma_f32_16x16x4_f32 v[8:11], v65, v33, v[8:11]
	v_mfma_f32_16x16x4_f32 v[8:11], v66, v34, v[8:11]
	v_mfma_f32_16x16x4_f32 v[8:11], v67, v35, v[8:11]
	v_mfma_f32_16x16x4_f32 v[8:11], v68, v36, v[8:11]
	v_mfma_f32_16x16x4_f32 v[8:11], v69, v37, v[8:11]
	v_mfma_f32_16x16x4_f32 v[8:11], v70, v38, v[8:11]
	v_mfma_f32_16x16x4_f32 v[8:11], v71, v39, v[8:11]
	global_load_dwordx4 v[28:31], v[4:5], off offset:1600
	global_load_dwordx4 v[32:35], v[6:7], off offset:3200
	global_load_dwordx4 v[36:39], v[6:7], off offset:3216
	s_waitcnt vmcnt(9)
	v_lshlrev_b32_e32 v64, 16, v40
	v_and_b32_e32 v65, 0xffff0000, v40
	v_lshlrev_b32_e32 v66, 16, v41
	v_and_b32_e32 v67, 0xffff0000, v41
	v_lshlrev_b32_e32 v68, 16, v42
	v_and_b32_e32 v69, 0xffff0000, v42
	v_lshlrev_b32_e32 v70, 16, v43
	v_and_b32_e32 v71, 0xffff0000, v43
	v_mfma_f32_16x16x4_f32 v[8:11], v64, v44, v[8:11]
	v_mfma_f32_16x16x4_f32 v[8:11], v65, v45, v[8:11]
	v_mfma_f32_16x16x4_f32 v[8:11], v66, v46, v[8:11]
	v_mfma_f32_16x16x4_f32 v[8:11], v67, v47, v[8:11]
	v_mfma_f32_16x16x4_f32 v[8:11], v68, v48, v[8:11]
	v_mfma_f32_16x16x4_f32 v[8:11], v69, v49, v[8:11]
	v_mfma_f32_16x16x4_f32 v[8:11], v70, v50, v[8:11]
	v_mfma_f32_16x16x4_f32 v[8:11], v71, v51, v[8:11]
	global_load_dwordx4 v[40:43], v[4:5], off offset:1664
	global_load_dwordx4 v[44:47], v[6:7], off offset:3328
	global_load_dwordx4 v[48:51], v[6:7], off offset:3344
	s_waitcnt vmcnt(9)
	v_lshlrev_b32_e32 v64, 16, v52
	v_and_b32_e32 v65, 0xffff0000, v52
	v_lshlrev_b32_e32 v66, 16, v53
	v_and_b32_e32 v67, 0xffff0000, v53
	v_lshlrev_b32_e32 v68, 16, v54
	v_and_b32_e32 v69, 0xffff0000, v54
	v_lshlrev_b32_e32 v70, 16, v55
	v_and_b32_e32 v71, 0xffff0000, v55
	v_mfma_f32_16x16x4_f32 v[8:11], v64, v56, v[8:11]
	v_mfma_f32_16x16x4_f32 v[8:11], v65, v57, v[8:11]
	v_mfma_f32_16x16x4_f32 v[8:11], v66, v58, v[8:11]
	v_mfma_f32_16x16x4_f32 v[8:11], v67, v59, v[8:11]
	v_mfma_f32_16x16x4_f32 v[8:11], v68, v60, v[8:11]
	v_mfma_f32_16x16x4_f32 v[8:11], v69, v61, v[8:11]
	v_mfma_f32_16x16x4_f32 v[8:11], v70, v62, v[8:11]
	v_mfma_f32_16x16x4_f32 v[8:11], v71, v63, v[8:11]
	global_load_dwordx4 v[52:55], v[4:5], off offset:1728
	global_load_dwordx4 v[56:59], v[6:7], off offset:3456
	global_load_dwordx4 v[60:63], v[6:7], off offset:3472
	s_waitcnt vmcnt(9)
; __device__ __forceinline__ float bf2f(bfu h) { return __uint_as_float(((unsigned)h) << 16); }
; #define SHX(v, m) shx_((v), (m), lane)
; __device__ void ba_item(const Params& p, int L, int rp) {
;     ...
;       _Pragma("unroll") for (int e = 0; e < 8; ++e) { hf[e] = bf2f((bfu)h0[u][e]); hf[8 + e] = bf2f((bfu)h1[u][e]); }
;       float a[8];
;       _Pragma("unroll") for (int j = 0; j < 8; ++j) {
;         float s = 0.f;
;         _Pragma("unroll") for (int e4 = 0; e4 < 4; ++e4) _Pragma("unroll") for (int e = 0; e < 4; ++e) s += hf[e4 * 4 + e] * wr_[j][e4][e];
;         _Pragma("unroll") for (int o = 32; o >= 1; o >>= 1) s += SHX(s, o);
;         a[j] = s;
	v_lshlrev_b32_e32 v64, 16, v16
	v_and_b32_e32 v65, 0xffff0000, v16
	v_lshlrev_b32_e32 v66, 16, v17
	v_and_b32_e32 v67, 0xffff0000, v17
	v_lshlrev_b32_e32 v68, 16, v18
	v_and_b32_e32 v69, 0xffff0000, v18
	v_lshlrev_b32_e32 v70, 16, v19
	v_and_b32_e32 v71, 0xffff0000, v19
	v_mfma_f32_16x16x4_f32 v[8:11], v64, v20, v[8:11]
	v_mfma_f32_16x16x4_f32 v[8:11], v65, v21, v[8:11]
	v_mfma_f32_16x16x4_f32 v[8:11], v66, v22, v[8:11]
	v_mfma_f32_16x16x4_f32 v[8:11], v67, v23, v[8:11]
	v_mfma_f32_16x16x4_f32 v[8:11], v68, v24, v[8:11]
	v_mfma_f32_16x16x4_f32 v[8:11], v69, v25, v[8:11]
	v_mfma_f32_16x16x4_f32 v[8:11], v70, v26, v[8:11]
	v_mfma_f32_16x16x4_f32 v[8:11], v71, v27, v[8:11]
	global_load_dwordx4 v[16:19], v[4:5], off offset:1792
	global_load_dwordx4 v[20:23], v[6:7], off offset:3584
	global_load_dwordx4 v[24:27], v[6:7], off offset:3600
	s_waitcnt vmcnt(9)
	v_lshlrev_b32_e32 v64, 16, v28
	v_and_b32_e32 v65, 0xffff0000, v28
	v_lshlrev_b32_e32 v66, 16, v29
	v_and_b32_e32 v67, 0xffff0000, v29
	v_lshlrev_b32_e32 v68, 16, v30
	v_and_b32_e32 v69, 0xffff0000, v30
	v_lshlrev_b32_e32 v70, 16, v31
	v_and_b32_e32 v71, 0xffff0000, v31
	v_mfma_f32_16x16x4_f32 v[8:11], v64, v32, v[8:11]
	v_mfma_f32_16x16x4_f32 v[8:11], v65, v33, v[8:11]
	v_mfma_f32_16x16x4_f32 v[8:11], v66, v34, v[8:11]
	v_mfma_f32_16x16x4_f32 v[8:11], v67, v35, v[8:11]
	v_mfma_f32_16x16x4_f32 v[8:11], v68, v36, v[8:11]
	v_mfma_f32_16x16x4_f32 v[8:11], v69, v37, v[8:11]
	v_mfma_f32_16x16x4_f32 v[8:11], v70, v38, v[8:11]
	v_mfma_f32_16x16x4_f32 v[8:11], v71, v39, v[8:11]
	global_load_dwordx4 v[28:31], v[4:5], off offset:1856
	global_load_dwordx4 v[32:35], v[6:7], off offset:3712
	global_load_dwordx4 v[36:39], v[6:7], off offset:3728
	s_waitcnt vmcnt(9)
	v_lshlrev_b32_e32 v64, 16, v40
	v_and_b32_e32 v65, 0xffff0000, v40
	v_lshlrev_b32_e32 v66, 16, v41
	v_and_b32_e32 v67, 0xffff0000, v41
	v_lshlrev_b32_e32 v68, 16, v42
	v_and_b32_e32 v69, 0xffff0000, v42
	v_lshlrev_b32_e32 v70, 16, v43
	v_and_b32_e32 v71, 0xffff0000, v43
	v_mfma_f32_16x16x4_f32 v[8:11], v64, v44, v[8:11]
	v_mfma_f32_16x16x4_f32 v[8:11], v65, v45, v[8:11]
	v_mfma_f32_16x16x4_f32 v[8:11], v66, v46, v[8:11]
	v_mfma_f32_16x16x4_f32 v[8:11], v67, v47, v[8:11]
	v_mfma_f32_16x16x4_f32 v[8:11], v68, v48, v[8:11]
	v_mfma_f32_16x16x4_f32 v[8:11], v69, v49, v[8:11]
	v_mfma_f32_16x16x4_f32 v[8:11], v70, v50, v[8:11]
	v_mfma_f32_16x16x4_f32 v[8:11], v71, v51, v[8:11]
	global_load_dwordx4 v[40:43], v[4:5], off offset:1920
	global_load_dwordx4 v[44:47], v[6:7], off offset:3840
	global_load_dwordx4 v[48:51], v[6:7], off offset:3856
	s_waitcnt vmcnt(9)
	v_lshlrev_b32_e32 v64, 16, v52
	v_and_b32_e32 v65, 0xffff0000, v52
	v_lshlrev_b32_e32 v66, 16, v53
	v_and_b32_e32 v67, 0xffff0000, v53
	v_lshlrev_b32_e32 v68, 16, v54
	v_and_b32_e32 v69, 0xffff0000, v54
	v_lshlrev_b32_e32 v70, 16, v55
	v_and_b32_e32 v71, 0xffff0000, v55
	v_mfma_f32_16x16x4_f32 v[8:11], v64, v56, v[8:11]
	v_mfma_f32_16x16x4_f32 v[8:11], v65, v57, v[8:11]
	v_mfma_f32_16x16x4_f32 v[8:11], v66, v58, v[8:11]
	v_mfma_f32_16x16x4_f32 v[8:11], v67, v59, v[8:11]
	v_mfma_f32_16x16x4_f32 v[8:11], v68, v60, v[8:11]
	v_mfma_f32_16x16x4_f32 v[8:11], v69, v61, v[8:11]
	v_mfma_f32_16x16x4_f32 v[8:11], v70, v62, v[8:11]
	v_mfma_f32_16x16x4_f32 v[8:11], v71, v63, v[8:11]
	global_load_dwordx4 v[52:55], v[4:5], off offset:1984
	global_load_dwordx4 v[56:59], v[6:7], off offset:3968
	global_load_dwordx4 v[60:63], v[6:7], off offset:3984
	s_waitcnt vmcnt(9)
	v_lshlrev_b32_e32 v64, 16, v16
	v_and_b32_e32 v65, 0xffff0000, v16
	v_lshlrev_b32_e32 v66, 16, v17
	v_and_b32_e32 v67, 0xffff0000, v17
	v_lshlrev_b32_e32 v68, 16, v18
	v_and_b32_e32 v69, 0xffff0000, v18
	v_lshlrev_b32_e32 v70, 16, v19
	v_and_b32_e32 v71, 0xffff0000, v19
	v_mfma_f32_16x16x4_f32 v[8:11], v64, v20, v[8:11]
	v_mfma_f32_16x16x4_f32 v[8:11], v65, v21, v[8:11]
	v_mfma_f32_16x16x4_f32 v[8:11], v66, v22, v[8:11]
	v_mfma_f32_16x16x4_f32 v[8:11], v67, v23, v[8:11]
	v_mfma_f32_16x16x4_f32 v[8:11], v68, v24, v[8:11]
	v_mfma_f32_16x16x4_f32 v[8:11], v69, v25, v[8:11]
	v_mfma_f32_16x16x4_f32 v[8:11], v70, v26, v[8:11]
	v_mfma_f32_16x16x4_f32 v[8:11], v71, v27, v[8:11]
	s_waitcnt vmcnt(6)
	v_lshlrev_b32_e32 v64, 16, v28
	v_and_b32_e32 v65, 0xffff0000, v28
	v_lshlrev_b32_e32 v66, 16, v29
	v_and_b32_e32 v67, 0xffff0000, v29
	v_lshlrev_b32_e32 v68, 16, v30
	v_and_b32_e32 v69, 0xffff0000, v30
	v_lshlrev_b32_e32 v70, 16, v31
	v_and_b32_e32 v71, 0xffff0000, v31
	v_mfma_f32_16x16x4_f32 v[8:11], v64, v32, v[8:11]
	v_mfma_f32_16x16x4_f32 v[8:11], v65, v33, v[8:11]
	v_mfma_f32_16x16x4_f32 v[8:11], v66, v34, v[8:11]
	v_mfma_f32_16x16x4_f32 v[8:11], v67, v35, v[8:11]
	v_mfma_f32_16x16x4_f32 v[8:11], v68, v36, v[8:11]
	v_mfma_f32_16x16x4_f32 v[8:11], v69, v37, v[8:11]
	v_mfma_f32_16x16x4_f32 v[8:11], v70, v38, v[8:11]
	v_mfma_f32_16x16x4_f32 v[8:11], v71, v39, v[8:11]
	s_waitcnt vmcnt(3)
	v_lshlrev_b32_e32 v64, 16, v40
	v_and_b32_e32 v65, 0xffff0000, v40
	v_lshlrev_b32_e32 v66, 16, v41
	v_and_b32_e32 v67, 0xffff0000, v41
	v_lshlrev_b32_e32 v68, 16, v42
	v_and_b32_e32 v69, 0xffff0000, v42
	v_lshlrev_b32_e32 v70, 16, v43
	v_and_b32_e32 v71, 0xffff0000, v43
	v_mfma_f32_16x16x4_f32 v[8:11], v64, v44, v[8:11]
	v_mfma_f32_16x16x4_f32 v[8:11], v65, v45, v[8:11]
	v_mfma_f32_16x16x4_f32 v[8:11], v66, v46, v[8:11]
	v_mfma_f32_16x16x4_f32 v[8:11], v67, v47, v[8:11]
	v_mfma_f32_16x16x4_f32 v[8:11], v68, v48, v[8:11]
	v_mfma_f32_16x16x4_f32 v[8:11], v69, v49, v[8:11]
	v_mfma_f32_16x16x4_f32 v[8:11], v70, v50, v[8:11]
	v_mfma_f32_16x16x4_f32 v[8:11], v71, v51, v[8:11]
	s_waitcnt vmcnt(0)
; __device__ __forceinline__ float fexp(float x) { return __builtin_amdgcn_exp2f(x * 1.4426950408889634f); }
; __device__ __forceinline__ float flog(float x) { return __builtin_amdgcn_logf(x) * 0.6931471805599453f; }
; __device__ __forceinline__ float frsq(float x) { return __builtin_amdgcn_rsqf(x); }
; __device__ __forceinline__ float sigmoidf_(float x) { return frcp(1.0f + fexp(-x)); }
; #define SHX(v, m) shx_((v), (m), lane)
; __device__ void ba_item(const Params& p, int L, int rp) {
;     ...
;       _Pragma("unroll") for (int j = 0; j < 8; ++j) {
;         float s = 0.f;
;         _Pragma("unroll") for (int e4 = 0; e4 < 4; ++e4) _Pragma("unroll") for (int e = 0; e < 4; ++e) s += hf[e4 * 4 + e] * wr_[j][e4][e];
;         _Pragma("unroll") for (int o = 32; o >= 1; o >>= 1) s += SHX(s, o);
;         a[j] = s;
;       }
;       if (lane < 8) {
;         float s16 = 0.f;
;         _Pragma("unroll") for (int i = 0; i < 4; ++i) s16 += (ps[u][i][0] + ps[u][i][1]) + (ps[u][i][2] + ps[u][i][3]);
;         float rs = frsq(s16 * (1.0f / 1024.0f) + 1e-6f);
;         float v = 0.f;
;         _Pragma("unroll") for (int j = 0; j < 8; ++j) if (lane == j) v = a[j];
;         v *= rs;
;         float r;
;         if (lane < 4) r = sigmoidf_(v);
;         else {
;           int hh = lane - 4;
;           float z = v + p.dn_dt_bias[(L >> 1) * 4 + hh];
;           float sp = (z > 20.f) ? z : flog(1.0f + fexp(z));
;           r = -fexp(p.dn_a_log[(L >> 1) * 4 + hh]) * sp;
;         }
;         miscw[MF_BG + (long)row * 8 + lane] = r;
;       }
	v_lshlrev_b32_e32 v64, 16, v52
	v_and_b32_e32 v65, 0xffff0000, v52
	v_lshlrev_b32_e32 v66, 16, v53
	v_and_b32_e32 v67, 0xffff0000, v53
	v_lshlrev_b32_e32 v68, 16, v54
	v_and_b32_e32 v69, 0xffff0000, v54
	v_lshlrev_b32_e32 v70, 16, v55
	v_and_b32_e32 v71, 0xffff0000, v55
	v_mfma_f32_16x16x4_f32 v[8:11], v64, v56, v[8:11]
	v_mfma_f32_16x16x4_f32 v[8:11], v65, v57, v[8:11]
	v_mfma_f32_16x16x4_f32 v[8:11], v66, v58, v[8:11]
	v_mfma_f32_16x16x4_f32 v[8:11], v67, v59, v[8:11]
	v_mfma_f32_16x16x4_f32 v[8:11], v68, v60, v[8:11]
	v_mfma_f32_16x16x4_f32 v[8:11], v69, v61, v[8:11]
	v_mfma_f32_16x16x4_f32 v[8:11], v70, v62, v[8:11]
	v_mfma_f32_16x16x4_f32 v[8:11], v71, v63, v[8:11]
	v_cmp_gt_u32_e32 vcc, 8, v2
	s_and_saveexec_b64 s[12:13], vcc
	s_nop 4
	v_add_f32_e32 v80, v80, v81
	v_add_f32_e32 v82, v82, v83
	v_add_f32_e32 v80, v80, v82
	v_add_f32_e32 v84, v84, v85
	v_add_f32_e32 v86, v86, v87
	v_add_f32_e32 v84, v84, v86
	v_add_f32_e32 v88, v88, v89
	v_add_f32_e32 v90, v90, v91
	v_add_f32_e32 v88, v88, v90
	v_add_f32_e32 v92, v92, v93
	v_add_f32_e32 v94, v94, v95
	v_add_f32_e32 v92, v92, v94
	v_add_f32_e32 v80, 0, v80
	v_add_f32_e32 v80, v84, v80
	v_add_f32_e32 v80, v88, v80
	v_add_f32_e32 v80, v92, v80
	v_fmamk_f32 v80, v80, 0x3a800000, v201
	v_rsq_f32_e32 v80, v80
	s_nop 0
	v_mul_f32_e32 v152, v8, v80
	v_mul_f32_e32 v153, 0xbfb8aa3b, v152
	v_exp_f32_e32 v153, v153
	s_nop 0
	v_add_f32_e32 v153, 1.0, v153
	v_rcp_f32_e32 v153, v153
	v_add_f32_e32 v154, v152, v150
	v_mul_f32_e32 v155, 0x3fb8aa3b, v154
	v_exp_f32_e32 v155, v155
	v_cmp_lt_f32_e64 s[0:1], s57, v154
	v_add_f32_e32 v155, 1.0, v155
	v_log_f32_e32 v155, v155
	s_nop 0
	v_mul_f32_e32 v155, 0x3f317218, v155
	v_cndmask_b32_e64 v154, v155, v154, s[0:1]
	v_mul_f32_e32 v155, 0x3fb8aa3b, v151
	v_exp_f32_e32 v155, v155
	s_nop 0
	v_mul_f32_e64 v154, v154, -v155
	v_cmp_gt_u32_e64 s[0:1], 4, v146
	s_nop 1
	v_cndmask_b32_e64 v154, v154, v153, s[0:1]
	global_store_dword v[148:149], v154, off offset:0
	v_add_f32_e32 v96, v96, v97
	v_add_f32_e32 v98, v98, v99
	v_add_f32_e32 v96, v96, v98
	v_add_f32_e32 v100, v100, v101
	v_add_f32_e32 v102, v102, v103
	v_add_f32_e32 v100, v100, v102
	v_add_f32_e32 v104, v104, v105
	v_add_f32_e32 v106, v106, v107
	v_add_f32_e32 v104, v104, v106
	v_add_f32_e32 v108, v108, v109
	v_add_f32_e32 v110, v110, v111
	v_add_f32_e32 v108, v108, v110
	v_add_f32_e32 v96, 0, v96
	v_add_f32_e32 v96, v100, v96
	v_add_f32_e32 v96, v104, v96
	v_add_f32_e32 v96, v108, v96
	v_fmamk_f32 v96, v96, 0x3a800000, v201
	v_rsq_f32_e32 v96, v96
	s_nop 0
	v_mul_f32_e32 v152, v9, v96
	v_mul_f32_e32 v153, 0xbfb8aa3b, v152
	v_exp_f32_e32 v153, v153
	s_nop 0
	v_add_f32_e32 v153, 1.0, v153
	v_rcp_f32_e32 v153, v153
	v_add_f32_e32 v154, v152, v150
	v_mul_f32_e32 v155, 0x3fb8aa3b, v154
	v_exp_f32_e32 v155, v155
	v_cmp_lt_f32_e64 s[0:1], s57, v154
	v_add_f32_e32 v155, 1.0, v155
	v_log_f32_e32 v155, v155
	s_nop 0
	v_mul_f32_e32 v155, 0x3f317218, v155
	v_cndmask_b32_e64 v154, v155, v154, s[0:1]
	v_mul_f32_e32 v155, 0x3fb8aa3b, v151
	v_exp_f32_e32 v155, v155
	s_nop 0
	v_mul_f32_e64 v154, v154, -v155
	v_cmp_gt_u32_e64 s[0:1], 4, v146
	s_nop 1
	v_cndmask_b32_e64 v154, v154, v153, s[0:1]
	global_store_dword v[148:149], v154, off offset:32
	v_add_f32_e32 v112, v112, v113
	v_add_f32_e32 v114, v114, v115
	v_add_f32_e32 v112, v112, v114
	v_add_f32_e32 v116, v116, v117
	v_add_f32_e32 v118, v118, v119
	v_add_f32_e32 v116, v116, v118
	v_add_f32_e32 v120, v120, v121
	v_add_f32_e32 v122, v122, v123
	v_add_f32_e32 v120, v120, v122
	v_add_f32_e32 v124, v124, v125
	v_add_f32_e32 v126, v126, v127
	v_add_f32_e32 v124, v124, v126
	v_add_f32_e32 v112, 0, v112
	v_add_f32_e32 v112, v116, v112
	v_add_f32_e32 v112, v120, v112
	v_add_f32_e32 v112, v124, v112
	v_fmamk_f32 v112, v112, 0x3a800000, v201
	v_rsq_f32_e32 v112, v112
	s_nop 0
	v_mul_f32_e32 v152, v10, v112
	v_mul_f32_e32 v153, 0xbfb8aa3b, v152
	v_exp_f32_e32 v153, v153
	s_nop 0
	v_add_f32_e32 v153, 1.0, v153
	v_rcp_f32_e32 v153, v153
	v_add_f32_e32 v154, v152, v150
	v_mul_f32_e32 v155, 0x3fb8aa3b, v154
	v_exp_f32_e32 v155, v155
	v_cmp_lt_f32_e64 s[0:1], s57, v154
	v_add_f32_e32 v155, 1.0, v155
	v_log_f32_e32 v155, v155
	s_nop 0
	v_mul_f32_e32 v155, 0x3f317218, v155
	v_cndmask_b32_e64 v154, v155, v154, s[0:1]
	v_mul_f32_e32 v155, 0x3fb8aa3b, v151
	v_exp_f32_e32 v155, v155
	s_nop 0
	v_mul_f32_e64 v154, v154, -v155
	v_cmp_gt_u32_e64 s[0:1], 4, v146
	s_nop 1
	v_cndmask_b32_e64 v154, v154, v153, s[0:1]
	global_store_dword v[148:149], v154, off offset:64
	v_add_f32_e32 v128, v128, v129
	v_add_f32_e32 v130, v130, v131
	v_add_f32_e32 v128, v128, v130
	v_add_f32_e32 v132, v132, v133
	v_add_f32_e32 v134, v134, v135
	v_add_f32_e32 v132, v132, v134
	v_add_f32_e32 v136, v136, v137
	v_add_f32_e32 v138, v138, v139
	v_add_f32_e32 v136, v136, v138
	v_add_f32_e32 v140, v140, v141
	v_add_f32_e32 v142, v142, v143
	v_add_f32_e32 v140, v140, v142
	v_add_f32_e32 v128, 0, v128
	v_add_f32_e32 v128, v132, v128
	v_add_f32_e32 v128, v136, v128
	v_add_f32_e32 v128, v140, v128
	v_fmamk_f32 v128, v128, 0x3a800000, v201
	v_rsq_f32_e32 v128, v128
	s_nop 0
	v_mul_f32_e32 v152, v11, v128
	v_mul_f32_e32 v153, 0xbfb8aa3b, v152
	v_exp_f32_e32 v153, v153
	s_nop 0
	v_add_f32_e32 v153, 1.0, v153
	v_rcp_f32_e32 v153, v153
	v_add_f32_e32 v154, v152, v150
	v_mul_f32_e32 v155, 0x3fb8aa3b, v154
	v_exp_f32_e32 v155, v155
	v_cmp_lt_f32_e64 s[0:1], s57, v154
	v_add_f32_e32 v155, 1.0, v155
	v_log_f32_e32 v155, v155
	s_nop 0
	v_mul_f32_e32 v155, 0x3f317218, v155
	v_cndmask_b32_e64 v154, v155, v154, s[0:1]
	v_mul_f32_e32 v155, 0x3fb8aa3b, v151
	v_exp_f32_e32 v155, v155
	s_nop 0
	v_mul_f32_e64 v154, v154, -v155
	v_cmp_gt_u32_e64 s[0:1], 4, v146
	s_nop 1
	v_cndmask_b32_e64 v154, v154, v153, s[0:1]
	global_store_dword v[148:149], v154, off offset:96
	s_or_b64 exec, exec, s[12:13]
	s_branch .LBB0_627
